# first grid barrier: one-time census (16 per-XCC counters + grid-dims scalar load) read speculatively at the start of the P0 RMSNorm part; used at the barrier if complete, original poll loop as fallbac
# speedup vs baseline: 1.0107x; 1.0107x over previous
; __device__ __forceinline__ unsigned pk2(float lo, float hi) { return pg8::cvt_pk_bf16(lo, hi); }
; __device__ __forceinline__ void rms_rows4_to_bf16(const float* xrow, const float* g, bf16* orow, int lane) {
;     f32x4 v[4][4]; float s[4];
; #pragma unroll
;     for (int r = 0; r < 4; ++r) { const f32x4* xr = (const f32x4*)(xrow + (size_t)r * DM) + lane;
; #pragma unroll
;         for (int j = 0; j < 4; ++j) v[r][j] = __builtin_nontemporal_load(xr + 64 * j); }
; #pragma unroll
;     for (int r = 0; r < 4; ++r) { float t = 0.f;
; #pragma unroll
;         for (int j = 0; j < 4; ++j) t += (v[r][j].x * v[r][j].x + v[r][j].y * v[r][j].y) + (v[r][j].z * v[r][j].z + v[r][j].w * v[r][j].w);
;         s[r] = t; }
; #pragma unroll
;     for (int o = 1; o < 64; o <<= 1) {
; #pragma unroll
;         for (int r = 0; r < 4; ++r) s[r] += __shfl_xor(s[r], o); }
;     const f32x4* gr = (const f32x4*)g + lane;
; #pragma unroll
;     for (int r = 0; r < 4; ++r) { const float rstd = __builtin_amdgcn_rsqf(s[r] * (1.f / DM) + pg8::RMS_EPS);
;         unsigned long long* o8 = (unsigned long long*)(orow + (size_t)r * DM) + lane;
; #pragma unroll
;         for (int j = 0; j < 4; ++j) { const f32x4 y = v[r][j] * rstd * gr[64 * j];
;             o8[64 * j] = (unsigned long long)pk2(y.x, y.y) | ((unsigned long long)pk2(y.z, y.w) << 32); } }
; }
; __global__ void __launch_bounds__(NWAVES * 64, 2) fwd_megakernel(Args a) {
;     ...
;         for (int m = gw * 4; m < M; m += NGW * 4) rms_rows4_to_bf16(a.x + (size_t)m * DM, a.norm_in, XN + (size_t)m * DM, lane);
.LBB0_67:
	v_readlane_b32 s2, v253, 25
	s_cmpk_gt_i32 s2, 0xfff
	v_readlane_b32 s3, v253, 26
	s_cbranch_scc1 .LBB0_70
	s_add_u32 s56, s96, 0x180400
	s_addc_u32 s57, s97, 0
	v_mov_b32_e32 v248, 0
	global_load_dword v232, v248, s[56:57] sc1
	global_load_dword v233, v248, s[56:57] offset:256 sc1
	global_load_dword v234, v248, s[56:57] offset:512 sc1
	global_load_dword v235, v248, s[56:57] offset:768 sc1
	global_load_dword v236, v248, s[56:57] offset:1024 sc1
	global_load_dword v237, v248, s[56:57] offset:1280 sc1
	global_load_dword v238, v248, s[56:57] offset:1536 sc1
	global_load_dword v239, v248, s[56:57] offset:1792 sc1
	global_load_dword v240, v248, s[56:57] offset:2048 sc1
	global_load_dword v241, v248, s[56:57] offset:2304 sc1
	global_load_dword v242, v248, s[56:57] offset:2560 sc1
	global_load_dword v243, v248, s[56:57] offset:2816 sc1
	global_load_dword v244, v248, s[56:57] offset:3072 sc1
	global_load_dword v245, v248, s[56:57] offset:3328 sc1
	global_load_dword v246, v248, s[56:57] offset:3584 sc1
	global_load_dword v247, v248, s[56:57] offset:3840 sc1
	s_load_dwordx2 s[58:59], s[48:49], 0x4
	v_readlane_b32 s2, v253, 25
	v_readlane_b32 s12, v253, 4
	v_readlane_b32 s13, v253, 5
	v_readlane_b32 s14, v253, 6
	v_readlane_b32 s15, v253, 7
	s_lshl_b32 s20, s2, 2
	s_lshl_b32 s21, s99, 5
	v_lshlrev_b32_e32 v98, 4, v231
	v_lshlrev_b32_e32 v99, 3, v231
	v_xor_b32_e32 v90, 1, v231
	v_lshlrev_b32_e32 v90, 2, v90
	v_xor_b32_e32 v91, 2, v231
	v_lshlrev_b32_e32 v91, 2, v91
	v_xor_b32_e32 v92, 4, v231
	v_lshlrev_b32_e32 v92, 2, v92
	v_xor_b32_e32 v93, 8, v231
	v_lshlrev_b32_e32 v93, 2, v93
	v_xor_b32_e32 v94, 16, v231
	v_lshlrev_b32_e32 v94, 2, v94
	v_xor_b32_e32 v95, 32, v231
	v_lshlrev_b32_e32 v95, 2, v95
	v_mov_b32_e32 v80, 0x3727c5ac
	global_load_dwordx4 v[0:3], v98, s[14:15] offset:0
	global_load_dwordx4 v[4:7], v98, s[14:15] offset:1024
	global_load_dwordx4 v[8:11], v98, s[14:15] offset:2048
	global_load_dwordx4 v[12:15], v98, s[14:15] offset:3072
	s_ashr_i32 s3, s20, 31
	s_mov_b32 s2, s20
	s_lshl_b64 s[2:3], s[2:3], 12
	s_add_u32 s4, s12, s2
	s_addc_u32 s5, s13, s3
	s_add_u32 s6, s4, 0x1000
	s_addc_u32 s7, s5, 0
	s_add_u32 s8, s4, 0x2000
	s_addc_u32 s9, s5, 0
	s_add_u32 s16, s4, 0x3000
	s_addc_u32 s17, s5, 0
	global_load_dwordx4 v[16:19], v98, s[4:5] offset:0 nt
	global_load_dwordx4 v[20:23], v98, s[4:5] offset:1024 nt
	global_load_dwordx4 v[24:27], v98, s[4:5] offset:2048 nt
	global_load_dwordx4 v[28:31], v98, s[4:5] offset:3072 nt
	global_load_dwordx4 v[32:35], v98, s[6:7] offset:0 nt
	global_load_dwordx4 v[36:39], v98, s[6:7] offset:1024 nt
	global_load_dwordx4 v[40:43], v98, s[6:7] offset:2048 nt
	global_load_dwordx4 v[44:47], v98, s[6:7] offset:3072 nt
	global_load_dwordx4 v[48:51], v98, s[8:9] offset:0 nt
	global_load_dwordx4 v[52:55], v98, s[8:9] offset:1024 nt
	global_load_dwordx4 v[56:59], v98, s[8:9] offset:2048 nt
	global_load_dwordx4 v[60:63], v98, s[8:9] offset:3072 nt
	global_load_dwordx4 v[64:67], v98, s[16:17] offset:0 nt
	global_load_dwordx4 v[68:71], v98, s[16:17] offset:1024 nt
	global_load_dwordx4 v[72:75], v98, s[16:17] offset:2048 nt
	global_load_dwordx4 v[76:79], v98, s[16:17] offset:3072 nt
	s_ashr_i32 s3, s20, 31
	s_mov_b32 s2, s20
	s_lshl_b64 s[2:3], s[2:3], 11
	s_add_u32 s18, s96, s2
	s_addc_u32 s19, s97, s3
	s_add_u32 s18, s18, 0x1800000
	s_addc_u32 s19, s19, 0
	s_add_u32 s22, s18, 0x1000
	s_addc_u32 s23, s19, 0
	s_ashr_i32 s3, s21, 31
	s_mov_b32 s2, s21
	s_lshl_b64 s[26:27], s[2:3], 12
	s_lshl_b64 s[2:3], s[2:3], 11
	s_waitcnt vmcnt(12)
	v_pk_mul_f32 v[96:97], v[16:17], v[16:17]
	v_pk_fma_f32 v[96:97], v[18:19], v[18:19], v[96:97]
	v_pk_fma_f32 v[96:97], v[20:21], v[20:21], v[96:97]
	v_pk_fma_f32 v[96:97], v[22:23], v[22:23], v[96:97]
	v_pk_fma_f32 v[96:97], v[24:25], v[24:25], v[96:97]
	v_pk_fma_f32 v[96:97], v[26:27], v[26:27], v[96:97]
	v_pk_fma_f32 v[96:97], v[28:29], v[28:29], v[96:97]
	v_pk_fma_f32 v[96:97], v[30:31], v[30:31], v[96:97]
	v_add_f32_e32 v82, v96, v97
	s_waitcnt vmcnt(8)
	v_pk_mul_f32 v[96:97], v[32:33], v[32:33]
	v_pk_fma_f32 v[96:97], v[34:35], v[34:35], v[96:97]
	v_pk_fma_f32 v[96:97], v[36:37], v[36:37], v[96:97]
	v_pk_fma_f32 v[96:97], v[38:39], v[38:39], v[96:97]
	v_pk_fma_f32 v[96:97], v[40:41], v[40:41], v[96:97]
	v_pk_fma_f32 v[96:97], v[42:43], v[42:43], v[96:97]
	v_pk_fma_f32 v[96:97], v[44:45], v[44:45], v[96:97]
	v_pk_fma_f32 v[96:97], v[46:47], v[46:47], v[96:97]
	v_add_f32_e32 v84, v96, v97
	s_waitcnt vmcnt(4)
; __device__ __forceinline__ unsigned pk2(float lo, float hi) { return pg8::cvt_pk_bf16(lo, hi); }
; __device__ __forceinline__ void rms_rows4_to_bf16(const float* xrow, const float* g, bf16* orow, int lane) {
;     ...
;     for (int r = 0; r < 4; ++r) { float t = 0.f;
; #pragma unroll
;         for (int j = 0; j < 4; ++j) t += (v[r][j].x * v[r][j].x + v[r][j].y * v[r][j].y) + (v[r][j].z * v[r][j].z + v[r][j].w * v[r][j].w);
;         s[r] = t; }
; #pragma unroll
;     for (int o = 1; o < 64; o <<= 1) {
; #pragma unroll
;         for (int r = 0; r < 4; ++r) s[r] += __shfl_xor(s[r], o); }
;     const f32x4* gr = (const f32x4*)g + lane;
; #pragma unroll
;     for (int r = 0; r < 4; ++r) { const float rstd = __builtin_amdgcn_rsqf(s[r] * (1.f / DM) + pg8::RMS_EPS);
;         unsigned long long* o8 = (unsigned long long*)(orow + (size_t)r * DM) + lane;
; #pragma unroll
;         for (int j = 0; j < 4; ++j) { const f32x4 y = v[r][j] * rstd * gr[64 * j];
;             o8[64 * j] = (unsigned long long)pk2(y.x, y.y) | ((unsigned long long)pk2(y.z, y.w) << 32); } }
; }
	v_pk_mul_f32 v[96:97], v[48:49], v[48:49]
	v_pk_fma_f32 v[96:97], v[50:51], v[50:51], v[96:97]
	v_pk_fma_f32 v[96:97], v[52:53], v[52:53], v[96:97]
	v_pk_fma_f32 v[96:97], v[54:55], v[54:55], v[96:97]
	v_pk_fma_f32 v[96:97], v[56:57], v[56:57], v[96:97]
	v_pk_fma_f32 v[96:97], v[58:59], v[58:59], v[96:97]
	v_pk_fma_f32 v[96:97], v[60:61], v[60:61], v[96:97]
	v_pk_fma_f32 v[96:97], v[62:63], v[62:63], v[96:97]
	v_add_f32_e32 v86, v96, v97
	s_waitcnt vmcnt(0)
	v_pk_mul_f32 v[96:97], v[64:65], v[64:65]
	v_pk_fma_f32 v[96:97], v[66:67], v[66:67], v[96:97]
	v_pk_fma_f32 v[96:97], v[68:69], v[68:69], v[96:97]
	v_pk_fma_f32 v[96:97], v[70:71], v[70:71], v[96:97]
	v_pk_fma_f32 v[96:97], v[72:73], v[72:73], v[96:97]
	v_pk_fma_f32 v[96:97], v[74:75], v[74:75], v[96:97]
	v_pk_fma_f32 v[96:97], v[76:77], v[76:77], v[96:97]
	v_pk_fma_f32 v[96:97], v[78:79], v[78:79], v[96:97]
	v_add_f32_e32 v88, v96, v97
	ds_bpermute_b32 v83, v90, v82
	ds_bpermute_b32 v85, v90, v84
	ds_bpermute_b32 v87, v90, v86
	ds_bpermute_b32 v89, v90, v88
	s_waitcnt lgkmcnt(3)
	v_add_f32_e32 v82, v82, v83
	s_waitcnt lgkmcnt(2)
	v_add_f32_e32 v84, v84, v85
	s_waitcnt lgkmcnt(1)
	v_add_f32_e32 v86, v86, v87
	s_waitcnt lgkmcnt(0)
	v_add_f32_e32 v88, v88, v89
	ds_bpermute_b32 v83, v91, v82
	ds_bpermute_b32 v85, v91, v84
	ds_bpermute_b32 v87, v91, v86
	ds_bpermute_b32 v89, v91, v88
	s_waitcnt lgkmcnt(3)
	v_add_f32_e32 v82, v82, v83
	s_waitcnt lgkmcnt(2)
	v_add_f32_e32 v84, v84, v85
	s_waitcnt lgkmcnt(1)
	v_add_f32_e32 v86, v86, v87
	s_waitcnt lgkmcnt(0)
	v_add_f32_e32 v88, v88, v89
	ds_bpermute_b32 v83, v92, v82
	ds_bpermute_b32 v85, v92, v84
	ds_bpermute_b32 v87, v92, v86
	ds_bpermute_b32 v89, v92, v88
	s_waitcnt lgkmcnt(3)
	v_add_f32_e32 v82, v82, v83
	s_waitcnt lgkmcnt(2)
	v_add_f32_e32 v84, v84, v85
	s_waitcnt lgkmcnt(1)
	v_add_f32_e32 v86, v86, v87
	s_waitcnt lgkmcnt(0)
	v_add_f32_e32 v88, v88, v89
	ds_bpermute_b32 v83, v93, v82
	ds_bpermute_b32 v85, v93, v84
	ds_bpermute_b32 v87, v93, v86
	ds_bpermute_b32 v89, v93, v88
	s_waitcnt lgkmcnt(3)
	v_add_f32_e32 v82, v82, v83
	s_waitcnt lgkmcnt(2)
	v_add_f32_e32 v84, v84, v85
	s_waitcnt lgkmcnt(1)
	v_add_f32_e32 v86, v86, v87
	s_waitcnt lgkmcnt(0)
	v_add_f32_e32 v88, v88, v89
	ds_bpermute_b32 v83, v94, v82
	ds_bpermute_b32 v85, v94, v84
	ds_bpermute_b32 v87, v94, v86
	ds_bpermute_b32 v89, v94, v88
	s_waitcnt lgkmcnt(3)
	v_add_f32_e32 v82, v82, v83
	s_waitcnt lgkmcnt(2)
	v_add_f32_e32 v84, v84, v85
	s_waitcnt lgkmcnt(1)
	v_add_f32_e32 v86, v86, v87
	s_waitcnt lgkmcnt(0)
	v_add_f32_e32 v88, v88, v89
	ds_bpermute_b32 v83, v95, v82
	ds_bpermute_b32 v85, v95, v84
	ds_bpermute_b32 v87, v95, v86
	ds_bpermute_b32 v89, v95, v88
	s_waitcnt lgkmcnt(3)
	v_add_f32_e32 v82, v82, v83
	s_waitcnt lgkmcnt(2)
	v_add_f32_e32 v84, v84, v85
	s_waitcnt lgkmcnt(1)
	v_add_f32_e32 v86, v86, v87
	s_waitcnt lgkmcnt(0)
	v_add_f32_e32 v88, v88, v89
	v_fmamk_f32 v82, v82, 0x3a800000, v80
	v_fmamk_f32 v84, v84, 0x3a800000, v80
	v_fmamk_f32 v86, v86, 0x3a800000, v80
	v_fmamk_f32 v88, v88, 0x3a800000, v80
	v_rsq_f32_e32 v82, v82
	v_rsq_f32_e32 v84, v84
	v_rsq_f32_e32 v86, v86
	v_rsq_f32_e32 v88, v88
	s_nop 0
	s_add_i32 s20, s20, s21
	s_cmpk_lt_i32 s20, 0x4000
	s_cselect_b32 s24, 1, 0
	v_pk_mul_f32 v[16:17], v[16:17], v[82:83] op_sel_hi:[1,0]
	v_pk_mul_f32 v[18:19], v[18:19], v[82:83] op_sel_hi:[1,0]
	v_pk_mul_f32 v[16:17], v[0:1], v[16:17]
	v_pk_mul_f32 v[18:19], v[2:3], v[18:19]
	v_cvt_pk_bf16_f32 v16, v16, v17
	v_cvt_pk_bf16_f32 v17, v18, v19
	global_store_dwordx2 v99, v[16:17], s[18:19] offset:0
	v_pk_mul_f32 v[20:21], v[20:21], v[82:83] op_sel_hi:[1,0]
	v_pk_mul_f32 v[22:23], v[22:23], v[82:83] op_sel_hi:[1,0]
	v_pk_mul_f32 v[20:21], v[4:5], v[20:21]
	v_pk_mul_f32 v[22:23], v[6:7], v[22:23]
	v_cvt_pk_bf16_f32 v20, v20, v21
	v_cvt_pk_bf16_f32 v21, v22, v23
	global_store_dwordx2 v99, v[20:21], s[18:19] offset:512
	v_pk_mul_f32 v[24:25], v[24:25], v[82:83] op_sel_hi:[1,0]
	v_pk_mul_f32 v[26:27], v[26:27], v[82:83] op_sel_hi:[1,0]
	v_pk_mul_f32 v[24:25], v[8:9], v[24:25]
	v_pk_mul_f32 v[26:27], v[10:11], v[26:27]
	v_cvt_pk_bf16_f32 v24, v24, v25
	v_cvt_pk_bf16_f32 v25, v26, v27
	global_store_dwordx2 v99, v[24:25], s[18:19] offset:1024
	v_pk_mul_f32 v[28:29], v[28:29], v[82:83] op_sel_hi:[1,0]
	v_pk_mul_f32 v[30:31], v[30:31], v[82:83] op_sel_hi:[1,0]
	v_pk_mul_f32 v[28:29], v[12:13], v[28:29]
	v_pk_mul_f32 v[30:31], v[14:15], v[30:31]
	v_cvt_pk_bf16_f32 v28, v28, v29
	v_cvt_pk_bf16_f32 v29, v30, v31
	global_store_dwordx2 v99, v[28:29], s[18:19] offset:1536
	s_add_u32 s4, s4, s26
	s_addc_u32 s5, s5, s27
	s_cmp_eq_u32 s24, 0
	s_cbranch_scc1 .Lp0_f_np0
	global_load_dwordx4 v[16:19], v98, s[4:5] offset:0 nt
	global_load_dwordx4 v[20:23], v98, s[4:5] offset:1024 nt
	global_load_dwordx4 v[24:27], v98, s[4:5] offset:2048 nt
	global_load_dwordx4 v[28:31], v98, s[4:5] offset:3072 nt

; __device__ __forceinline__ unsigned xb_ld(unsigned* p)              { return __hip_atomic_load(p, __ATOMIC_RELAXED, __HIP_MEMORY_SCOPE_AGENT); }
; __device__ __forceinline__ void xcd_barrier_complete(unsigned* bar, unsigned x, unsigned& nloc, unsigned& nx) {
;     const unsigned G = gridDim.x * gridDim.y * gridDim.z;
;     unsigned sum, cnt, mine, sp = 0u;
;     for (;;) {
;         sum = 0u; cnt = 0u; mine = 0u;
; #pragma unroll
;         for (unsigned j = 0; j < 16; ++j) { const unsigned c = xb_ld(&bar[XB_XCNT(j)]); sum += c; cnt += (c > 0u) ? 1u : 0u; mine = (j == x) ? c : mine; }
;         if (sum == G) break;
;         __builtin_amdgcn_s_sleep(1);
;         if ((++sp & 255u) == 0u) { if (xb_ld(&bar[XB_TMO])) break; if (sp > XB_SPIN_CAP) { atomicAdd(&bar[XB_TMO], 1u); break; } }
;     }
;     nloc = mine > 0u ? mine : 1u; nx = cnt > 0u ? cnt : 1u;
; __device__ __forceinline__ void xcd_barrier(const XcdBarrier& b) {
;     ...
;     if (threadIdx.x == 0) {
;         unsigned* bar = b.bar;
;         __builtin_amdgcn_s_waitcnt(0);
;         unsigned nloc = b.st[0], nx = b.st[1];
;         if (nloc == 0u) { xcd_barrier_complete(bar, b.x, nloc, nx); b.st[0] = nloc; b.st[1] = nx; }
.LBB0_70:
	s_waitcnt vmcnt(0)
	s_barrier
	s_mov_b64 s[2:3], exec
	v_readlane_b32 s4, v253, 23
	v_readlane_b32 s5, v253, 24
	s_and_b64 s[4:5], s[2:3], s[4:5]
	s_mov_b64 exec, s[4:5]
	s_cbranch_execz .LBB0_122
	s_add_i32 s4, 0, 0x20420
	v_mov_b32_e32 v0, s4
	s_waitcnt vmcnt(0) expcnt(0) lgkmcnt(0)
	ds_read_b32 v2, v0
	s_add_i32 s4, 0, 0x20424
	v_mov_b32_e32 v0, s4
	ds_read_b32 v0, v0
	s_waitcnt lgkmcnt(1)
	v_cmp_ne_u32_e32 vcc, 0, v2
	s_cbranch_vccnz .LBB0_86
	s_mov_b64 s[8:9], s[58:59]
	s_add_u32 s4, s96, 0x180200
	s_addc_u32 s5, s97, 0
	s_add_u32 s6, s96, 0x180400
	s_addc_u32 s7, s97, 0
	s_waitcnt lgkmcnt(0)
	s_mul_i32 s33, s8, s99
	s_add_u32 s8, s96, 0x180500
	s_mul_i32 s33, s33, s9
	s_addc_u32 s9, s97, 0
	s_add_u32 s10, s96, 0x180600
	s_addc_u32 s11, s97, 0
	s_add_u32 s12, s96, 0x180700
	s_addc_u32 s13, s97, 0
	s_add_u32 s14, s96, 0x180800
	s_addc_u32 s15, s97, 0
	s_add_u32 s16, s96, 0x180900
	s_addc_u32 s17, s97, 0
	s_add_u32 s18, s96, 0x180a00
	s_addc_u32 s19, s97, 0
	s_add_u32 s20, s96, 0x180b00
	s_addc_u32 s21, s97, 0
	s_add_u32 s22, s96, 0x180c00
	s_addc_u32 s23, s97, 0
	s_add_u32 s24, s96, 0x180d00
	s_addc_u32 s25, s97, 0
	s_add_u32 s26, s96, 0x180e00
	s_addc_u32 s27, s97, 0
	s_add_u32 s28, s96, 0x180f00
	s_addc_u32 s29, s97, 0
	s_add_u32 s30, s96, 0x181000
	s_addc_u32 s31, s97, 0
	s_add_u32 s34, s96, 0x181100
	s_addc_u32 s35, s97, 0
	s_add_u32 s36, s96, 0x181200
	s_addc_u32 s37, s97, 0
	s_add_u32 s38, s96, 0x181300
	s_addc_u32 s39, s97, 0
	s_mov_b32 s46, 1
	v_mov_b32_e32 v16, 0
	v_mov_b32_e32 v15, v232
	v_mov_b32_e32 v0, v233
	v_mov_b32_e32 v1, v234
	v_mov_b32_e32 v2, v235
	v_mov_b32_e32 v3, v236
	v_mov_b32_e32 v4, v237
	v_mov_b32_e32 v5, v238
	v_mov_b32_e32 v6, v239
	v_mov_b32_e32 v7, v240
	v_mov_b32_e32 v8, v241
	v_mov_b32_e32 v9, v242
	v_mov_b32_e32 v10, v243
	v_mov_b32_e32 v11, v244
	v_mov_b32_e32 v12, v245
	v_mov_b32_e32 v13, v246
	v_mov_b32_e32 v14, v247
	v_add_u32_e32 v17, v0, v15
	v_add_u32_e32 v17, v17, v1
	v_add_u32_e32 v17, v17, v2
	v_add_u32_e32 v17, v17, v3
	v_add_u32_e32 v17, v17, v4
	v_add_u32_e32 v17, v17, v5
	v_add_u32_e32 v17, v17, v6
	v_add_u32_e32 v17, v17, v7
	v_add_u32_e32 v17, v17, v8
	v_add_u32_e32 v17, v17, v9
	v_add_u32_e32 v17, v17, v10
	v_add_u32_e32 v17, v17, v11
	v_add_u32_e32 v17, v17, v12
	v_add_u32_e32 v17, v17, v13
	v_add_u32_e32 v17, v17, v14
	s_mov_b64 s[40:41], -1
	s_mov_b64 s[42:43], -1
	v_cmp_eq_u32_e32 vcc, s33, v17
	s_cbranch_vccnz .LBB0_73
	s_branch .LBB0_74
